# all four GEMM K-loops staged with LDS-DMA (global_load_lds, 2 stages) instead of register staging + ds_write
# speedup vs baseline: 1.0511x; 1.0086x over previous
.LBB0_654:
	s_lshl_b32 s4, s14, 3
	s_and_b32 s4, s4, 56
	s_ashr_i32 s5, s14, 6
	s_add_i32 s4, s4, s5
	s_lshl_b32 s16, s4, 8
	s_lshl_b32 s4, s14, 4
	s_and_b32 s15, s4, 0x380
	v_readfirstlane_b32 s101, v175
	v_lshrrev_b32_e32 v119, 3, v175
	v_and_b32_e32 v119, 6, v119
	s_movk_i32 s100, 0x78
	v_lshrrev_b32_e64 v119, v119, s100
	v_xor_b32_e32 v119, v119, v175
	v_and_b32_e32 v119, 3, v119
	v_lshlrev_b32_e32 v119, 4, v119
	v_lshrrev_b32_e32 v120, 2, v175
	v_lshl_or_b32 v114, v120, 11, v119
	v_add_u32_e32 v115, 0x20000, v114
	v_add_u32_e32 v116, 0x40000, v114
	v_add_u32_e32 v117, 0x60000, v114
	s_lshl_b32 s100, s16, 11
	s_add_u32 s4, s96, s100
	s_addc_u32 s5, s97, 0
	s_lshl_b32 s100, s15, 11
	s_add_u32 s10, s2, s100
	s_addc_u32 s11, s3, 0
	s_lshr_b32 s100, s101, 6
	s_lshl_b32 s18, s100, 10
	s_mov_b32 m0, s18
	s_nop 0
	global_load_lds_dwordx4 v114, s[4:5]
	s_add_u32 m0, s18, 4096
	s_nop 0
	global_load_lds_dwordx4 v115, s[4:5]
	s_add_u32 m0, s18, 8192
	s_nop 0
	global_load_lds_dwordx4 v116, s[4:5]
	s_add_u32 m0, s18, 12288
	s_nop 0
	global_load_lds_dwordx4 v117, s[4:5]
	s_add_u32 m0, s18, 16384
	s_nop 0
	global_load_lds_dwordx4 v114, s[10:11]
	s_add_u32 m0, s18, 20480
	s_nop 0
	global_load_lds_dwordx4 v115, s[10:11]
	s_add_u32 s4, s4, 64
	s_addc_u32 s5, s5, 0
	s_add_u32 s10, s10, 64
	s_addc_u32 s11, s11, 0
	s_add_u32 s18, s18, 24576
	s_cmp_ge_u32 s18, 49152
	s_cselect_b32 s100, 49152, 0
	s_sub_u32 s18, s18, s100
	v_and_b32_e32 v119, 15, v175
	s_and_b32 s100, s101, 64
	v_or_b32_e32 v120, s100, v119
	v_lshlrev_b32_e32 v158, 6, v120
	s_ashr_i32 s100, s101, 7
	s_mulk_i32 s100, 0x80
	v_or_b32_e32 v120, s100, v119
	v_lshlrev_b32_e32 v159, 6, v120
	v_lshrrev_b32_e32 v120, 1, v175
	v_and_b32_e32 v120, 6, v120
	s_movk_i32 s100, 0x78
	v_lshrrev_b32_e64 v120, v120, s100
	v_lshrrev_b32_e32 v121, 4, v175
	v_xor_b32_e32 v120, v120, v121
	v_lshlrev_b32_e32 v120, 4, v120
	v_and_b32_e32 v160, 48, v120
	v_mov_b32_e32 v150, 0
	v_mov_b32_e32 v151, 0
	v_mov_b32_e32 v152, 0
	v_mov_b32_e32 v153, 0
	v_mov_b32_e32 v146, 0
	v_mov_b32_e32 v147, 0
	v_mov_b32_e32 v148, 0
	v_mov_b32_e32 v149, 0
	v_mov_b32_e32 v142, 0
	v_mov_b32_e32 v143, 0
	v_mov_b32_e32 v144, 0
	v_mov_b32_e32 v145, 0
	v_mov_b32_e32 v138, 0
	v_mov_b32_e32 v139, 0
	v_mov_b32_e32 v140, 0
	v_mov_b32_e32 v141, 0
	v_mov_b32_e32 v110, 0
	v_mov_b32_e32 v111, 0
	v_mov_b32_e32 v112, 0
	v_mov_b32_e32 v113, 0
	v_mov_b32_e32 v106, 0
	v_mov_b32_e32 v107, 0
	v_mov_b32_e32 v108, 0
	v_mov_b32_e32 v109, 0
	v_mov_b32_e32 v102, 0
	v_mov_b32_e32 v103, 0
	v_mov_b32_e32 v104, 0
	v_mov_b32_e32 v105, 0
	v_mov_b32_e32 v98, 0
	v_mov_b32_e32 v99, 0
	v_mov_b32_e32 v100, 0
	v_mov_b32_e32 v101, 0
	v_mov_b32_e32 v94, 0
	v_mov_b32_e32 v95, 0
	v_mov_b32_e32 v96, 0
	v_mov_b32_e32 v97, 0
	v_mov_b32_e32 v90, 0
	v_mov_b32_e32 v91, 0
	v_mov_b32_e32 v92, 0
	v_mov_b32_e32 v93, 0
	v_mov_b32_e32 v86, 0
	v_mov_b32_e32 v87, 0
	v_mov_b32_e32 v88, 0
	v_mov_b32_e32 v89, 0
	v_mov_b32_e32 v82, 0
	v_mov_b32_e32 v83, 0
	v_mov_b32_e32 v84, 0
	v_mov_b32_e32 v85, 0
	v_mov_b32_e32 v78, 0
	v_mov_b32_e32 v79, 0
	v_mov_b32_e32 v80, 0
	v_mov_b32_e32 v81, 0
	v_mov_b32_e32 v74, 0
	v_mov_b32_e32 v75, 0
	v_mov_b32_e32 v76, 0
	v_mov_b32_e32 v77, 0
	v_mov_b32_e32 v70, 0
	v_mov_b32_e32 v71, 0
	v_mov_b32_e32 v72, 0
	v_mov_b32_e32 v73, 0
	v_mov_b32_e32 v66, 0
	v_mov_b32_e32 v67, 0
	v_mov_b32_e32 v68, 0
	v_mov_b32_e32 v69, 0
	v_mov_b32_e32 v62, 0
	v_mov_b32_e32 v63, 0
	v_mov_b32_e32 v64, 0
	v_mov_b32_e32 v65, 0
	v_mov_b32_e32 v58, 0
	v_mov_b32_e32 v59, 0
	v_mov_b32_e32 v60, 0
	v_mov_b32_e32 v61, 0
	v_mov_b32_e32 v54, 0
	v_mov_b32_e32 v55, 0
	v_mov_b32_e32 v56, 0
	v_mov_b32_e32 v57, 0
	v_mov_b32_e32 v50, 0
	v_mov_b32_e32 v51, 0
	v_mov_b32_e32 v52, 0
	v_mov_b32_e32 v53, 0
	v_mov_b32_e32 v46, 0
	v_mov_b32_e32 v47, 0
	v_mov_b32_e32 v48, 0
	v_mov_b32_e32 v49, 0
	v_mov_b32_e32 v42, 0
	v_mov_b32_e32 v43, 0
	v_mov_b32_e32 v44, 0
	v_mov_b32_e32 v45, 0
	v_mov_b32_e32 v38, 0
	v_mov_b32_e32 v39, 0
	v_mov_b32_e32 v40, 0
	v_mov_b32_e32 v41, 0
	v_mov_b32_e32 v34, 0
	v_mov_b32_e32 v35, 0
	v_mov_b32_e32 v36, 0
	v_mov_b32_e32 v37, 0
	v_mov_b32_e32 v30, 0
	v_mov_b32_e32 v31, 0
	v_mov_b32_e32 v32, 0
	v_mov_b32_e32 v33, 0
	v_mov_b32_e32 v26, 0
	v_mov_b32_e32 v27, 0
	v_mov_b32_e32 v28, 0
	v_mov_b32_e32 v29, 0
	v_mov_b32_e32 v22, 0
	v_mov_b32_e32 v23, 0
	v_mov_b32_e32 v24, 0
	v_mov_b32_e32 v25, 0
	v_mov_b32_e32 v18, 0
	v_mov_b32_e32 v19, 0
	v_mov_b32_e32 v20, 0
	v_mov_b32_e32 v21, 0
	v_mov_b32_e32 v14, 0
	v_mov_b32_e32 v15, 0
	v_mov_b32_e32 v16, 0
	v_mov_b32_e32 v17, 0
	v_mov_b32_e32 v10, 0
	v_mov_b32_e32 v11, 0
	v_mov_b32_e32 v12, 0
	v_mov_b32_e32 v13, 0
	v_mov_b32_e32 v6, 0
	v_mov_b32_e32 v7, 0
	v_mov_b32_e32 v8, 0
	v_mov_b32_e32 v9, 0
	v_mov_b32_e32 v2, 0
	v_mov_b32_e32 v3, 0
	v_mov_b32_e32 v4, 0
	v_mov_b32_e32 v5, 0
	s_mov_b32 s19, 0
	s_mov_b32 s17, 0
	s_waitcnt vmcnt(0)
	s_barrier
.Lop8_loop:
	s_cmp_ge_u32 s17, 31
	s_cbranch_scc1 .Lop8_body
	s_mov_b32 m0, s18
	s_nop 0
	global_load_lds_dwordx4 v114, s[4:5]
	s_add_u32 m0, s18, 4096
	s_nop 0
	global_load_lds_dwordx4 v115, s[4:5]
	s_add_u32 m0, s18, 8192
	s_nop 0
	global_load_lds_dwordx4 v116, s[4:5]
	s_add_u32 m0, s18, 12288
	s_nop 0
	global_load_lds_dwordx4 v117, s[4:5]
	s_add_u32 m0, s18, 16384
	s_nop 0
	global_load_lds_dwordx4 v114, s[10:11]
	s_add_u32 m0, s18, 20480
	s_nop 0
	global_load_lds_dwordx4 v115, s[10:11]
	s_add_u32 s4, s4, 64
	s_addc_u32 s5, s5, 0
	s_add_u32 s10, s10, 64
	s_addc_u32 s11, s11, 0
	s_add_u32 s18, s18, 24576
	s_cmp_ge_u32 s18, 49152
	s_cselect_b32 s100, 49152, 0
	s_sub_u32 s18, s18, s100
.Lop8_body:
	v_add_u32_e32 v0, s19, v160
	v_add_u32_e32 v180, v0, v158
	ds_read_b128 v[162:165], v180 offset:16384
	ds_read_b128 v[166:169], v180 offset:17408
	ds_read_b128 v[176:179], v180 offset:18432
	ds_read_b128 v[180:183], v180 offset:19456
	v_add_u32_e32 v0, v0, v159
	ds_read_b128 v[170:173], v0
	ds_read_b128 v[184:187], v0 offset:1024
	ds_read_b128 v[188:191], v0 offset:2048
	s_waitcnt lgkmcnt(2)
	v_mfma_f32_16x16x32_bf16 v[150:153], v[162:165], v[170:173], v[150:153]
	v_mfma_f32_16x16x32_bf16 v[146:149], v[166:169], v[170:173], v[146:149]
	v_mfma_f32_16x16x32_bf16 v[142:145], v[176:179], v[170:173], v[142:145]
	v_mfma_f32_16x16x32_bf16 v[138:141], v[180:183], v[170:173], v[138:141]
	ds_read_b128 v[170:173], v0 offset:3072
	s_waitcnt lgkmcnt(2)
	v_mfma_f32_16x16x32_bf16 v[110:113], v[162:165], v[184:187], v[110:113]
	v_mfma_f32_16x16x32_bf16 v[106:109], v[166:169], v[184:187], v[106:109]
	v_mfma_f32_16x16x32_bf16 v[102:105], v[176:179], v[184:187], v[102:105]
	v_mfma_f32_16x16x32_bf16 v[98:101], v[180:183], v[184:187], v[98:101]
	ds_read_b128 v[184:187], v0 offset:4096
	s_waitcnt lgkmcnt(2)
	v_mfma_f32_16x16x32_bf16 v[94:97], v[162:165], v[188:191], v[94:97]
	v_mfma_f32_16x16x32_bf16 v[90:93], v[166:169], v[188:191], v[90:93]
	v_mfma_f32_16x16x32_bf16 v[86:89], v[176:179], v[188:191], v[86:89]
	v_mfma_f32_16x16x32_bf16 v[82:85], v[180:183], v[188:191], v[82:85]
	ds_read_b128 v[188:191], v0 offset:5120
	s_waitcnt lgkmcnt(2)
	v_mfma_f32_16x16x32_bf16 v[78:81], v[162:165], v[170:173], v[78:81]
	v_mfma_f32_16x16x32_bf16 v[74:77], v[166:169], v[170:173], v[74:77]
	v_mfma_f32_16x16x32_bf16 v[70:73], v[176:179], v[170:173], v[70:73]
	v_mfma_f32_16x16x32_bf16 v[66:69], v[180:183], v[170:173], v[66:69]
	ds_read_b128 v[170:173], v0 offset:6144
	s_waitcnt lgkmcnt(2)
	v_mfma_f32_16x16x32_bf16 v[62:65], v[162:165], v[184:187], v[62:65]
	v_mfma_f32_16x16x32_bf16 v[58:61], v[166:169], v[184:187], v[58:61]
	v_mfma_f32_16x16x32_bf16 v[54:57], v[176:179], v[184:187], v[54:57]
	v_mfma_f32_16x16x32_bf16 v[50:53], v[180:183], v[184:187], v[50:53]
	ds_read_b128 v[184:187], v0 offset:7168
	s_waitcnt lgkmcnt(2)
	v_mfma_f32_16x16x32_bf16 v[46:49], v[162:165], v[188:191], v[46:49]
	v_mfma_f32_16x16x32_bf16 v[42:45], v[166:169], v[188:191], v[42:45]
	v_mfma_f32_16x16x32_bf16 v[38:41], v[176:179], v[188:191], v[38:41]
	v_mfma_f32_16x16x32_bf16 v[34:37], v[180:183], v[188:191], v[34:37]
	s_waitcnt lgkmcnt(1)
	v_mfma_f32_16x16x32_bf16 v[30:33], v[162:165], v[170:173], v[30:33]
	v_mfma_f32_16x16x32_bf16 v[26:29], v[166:169], v[170:173], v[26:29]
	v_mfma_f32_16x16x32_bf16 v[22:25], v[176:179], v[170:173], v[22:25]
	v_mfma_f32_16x16x32_bf16 v[18:21], v[180:183], v[170:173], v[18:21]
	s_waitcnt lgkmcnt(0)
	v_mfma_f32_16x16x32_bf16 v[14:17], v[162:165], v[184:187], v[14:17]
	v_mfma_f32_16x16x32_bf16 v[10:13], v[166:169], v[184:187], v[10:13]
	v_mfma_f32_16x16x32_bf16 v[6:9], v[176:179], v[184:187], v[6:9]
	v_mfma_f32_16x16x32_bf16 v[2:5], v[180:183], v[184:187], v[2:5]
	s_xor_b32 s19, s19, 24576
	s_waitcnt vmcnt(0)
	s_barrier
	s_add_u32 s17, s17, 1
	s_cmp_lt_u32 s17, 32
	s_cbranch_scc1 .Lop8_loop

.LBB0_714:
	s_lshr_b32 s5, s11, 3
	s_and_b32 s5, s5, 7
	s_lshl_b32 s15, s5, 7
	s_lshl_b32 s5, s11, 3
	s_and_b32 s5, s5, 56
	s_bfe_u32 s17, s11, 0x30006
	s_bfe_u32 s16, s10, 0x30003
	s_or_b32 s12, s5, s17
	s_mulk_i32 s16, 0x900
	s_mulk_i32 s17, 0x120
	s_mulk_i32 s12, 0x120
	s_andn2_b64 vcc, exec, s[0:1]
	s_mov_b64 s[0:1], -1
	s_cbranch_vccz .LBB0_731
	v_readfirstlane_b32 s13, v175
	v_lshrrev_b32_e32 v55, 3, v175
	v_and_b32_e32 v55, 6, v55
	s_movk_i32 s16, 0x78
	v_lshrrev_b32_e64 v55, v55, s16
	v_xor_b32_e32 v55, v55, v175
	v_and_b32_e32 v55, 3, v55
	v_lshlrev_b32_e32 v55, 4, v55
	v_lshrrev_b32_e32 v56, 2, v175
	v_lshl_or_b32 v50, v56, 11, v55
	v_add_u32_e32 v51, 0x20000, v50
	v_add_u32_e32 v52, 0x40000, v50
	v_add_u32_e32 v53, 0x60000, v50
	v_add_u32_e32 v54, 0x80000, v50
	s_lshl_b32 s16, s12, 11
	s_add_u32 s6, s96, s16
	s_addc_u32 s7, s97, 0
	v_readlane_b32 s8, v252, 52
	v_readlane_b32 s9, v252, 53
	s_lshl_b32 s16, s14, 11
	s_add_u32 s8, s8, s16
	s_addc_u32 s9, s9, 0
	s_lshr_b32 s16, s13, 6
	s_lshl_b32 s18, s16, 10
	s_cmpk_lt_i32 s13, 0x80
	s_cselect_b32 s15, 1, 0
	s_mov_b32 m0, s18
	s_nop 0
	global_load_lds_dwordx4 v50, s[6:7]
	s_add_u32 m0, s18, 4096
	s_nop 0
	global_load_lds_dwordx4 v51, s[6:7]
	s_add_u32 m0, s18, 8192
	s_nop 0
	global_load_lds_dwordx4 v52, s[6:7]
	s_add_u32 m0, s18, 12288
	s_nop 0
	global_load_lds_dwordx4 v53, s[6:7]
	s_cmp_eq_u32 s15, 0
	s_cbranch_scc1 .Lipa_noremp
	s_add_u32 m0, s18, 16384
	s_nop 0
	global_load_lds_dwordx4 v54, s[6:7]
.Lipa_noremp:
	s_add_u32 m0, s18, 18432
	s_nop 0
	global_load_lds_dwordx4 v50, s[8:9]
	s_add_u32 m0, s18, 22528
	s_nop 0
	global_load_lds_dwordx4 v51, s[8:9]
	s_add_u32 s6, s6, 64
	s_addc_u32 s7, s7, 0
	s_add_u32 s8, s8, 64
	s_addc_u32 s9, s9, 0
	s_add_u32 s18, s18, 26624
	s_cmp_ge_u32 s18, 53248
	s_cselect_b32 s16, 53248, 0
	s_sub_u32 s18, s18, s16
	v_and_b32_e32 v55, 15, v175
	s_and_b32 s16, s13, 64
	v_or_b32_e32 v56, s16, v55
	v_lshlrev_b32_e32 v180, 6, v56
	s_ashr_i32 s16, s13, 7
	s_mulk_i32 s16, 0x90
	v_or_b32_e32 v56, s16, v55
	v_lshlrev_b32_e32 v181, 6, v56
	v_lshrrev_b32_e32 v56, 1, v175
	v_and_b32_e32 v56, 6, v56
	s_movk_i32 s16, 0x78
	v_lshrrev_b32_e64 v56, v56, s16
	v_lshrrev_b32_e32 v57, 4, v175
	v_xor_b32_e32 v56, v56, v57
	v_lshlrev_b32_e32 v56, 4, v56
	v_and_b32_e32 v182, 48, v56
	v_mov_b32_e32 v170, 0
	v_mov_b32_e32 v171, 0
	v_mov_b32_e32 v172, 0
	v_mov_b32_e32 v173, 0
	v_mov_b32_e32 v166, 0
	v_mov_b32_e32 v167, 0
	v_mov_b32_e32 v168, 0
	v_mov_b32_e32 v169, 0
	v_mov_b32_e32 v162, 0
	v_mov_b32_e32 v163, 0
	v_mov_b32_e32 v164, 0
	v_mov_b32_e32 v165, 0
	v_mov_b32_e32 v158, 0
	v_mov_b32_e32 v159, 0
	v_mov_b32_e32 v160, 0
	v_mov_b32_e32 v161, 0
	v_mov_b32_e32 v154, 0
	v_mov_b32_e32 v155, 0
	v_mov_b32_e32 v156, 0
	v_mov_b32_e32 v157, 0
	v_mov_b32_e32 v150, 0
	v_mov_b32_e32 v151, 0
	v_mov_b32_e32 v152, 0
	v_mov_b32_e32 v153, 0
	v_mov_b32_e32 v146, 0
	v_mov_b32_e32 v147, 0
	v_mov_b32_e32 v148, 0
	v_mov_b32_e32 v149, 0
	v_mov_b32_e32 v142, 0
	v_mov_b32_e32 v143, 0
	v_mov_b32_e32 v144, 0
	v_mov_b32_e32 v145, 0
	v_mov_b32_e32 v138, 0
	v_mov_b32_e32 v139, 0
	v_mov_b32_e32 v140, 0
	v_mov_b32_e32 v141, 0
	v_mov_b32_e32 v134, 0
	v_mov_b32_e32 v135, 0
	v_mov_b32_e32 v136, 0
	v_mov_b32_e32 v137, 0
	v_mov_b32_e32 v130, 0
	v_mov_b32_e32 v131, 0
	v_mov_b32_e32 v132, 0
	v_mov_b32_e32 v133, 0
	v_mov_b32_e32 v126, 0
	v_mov_b32_e32 v127, 0
	v_mov_b32_e32 v128, 0
	v_mov_b32_e32 v129, 0
	v_mov_b32_e32 v122, 0
	v_mov_b32_e32 v123, 0
	v_mov_b32_e32 v124, 0
	v_mov_b32_e32 v125, 0
	v_mov_b32_e32 v114, 0
	v_mov_b32_e32 v115, 0
	v_mov_b32_e32 v116, 0
	v_mov_b32_e32 v117, 0
	v_mov_b32_e32 v110, 0
	v_mov_b32_e32 v111, 0
	v_mov_b32_e32 v112, 0
	v_mov_b32_e32 v113, 0
	v_mov_b32_e32 v106, 0
	v_mov_b32_e32 v107, 0
	v_mov_b32_e32 v108, 0
	v_mov_b32_e32 v109, 0
	v_mov_b32_e32 v98, 0
	v_mov_b32_e32 v99, 0
	v_mov_b32_e32 v100, 0
	v_mov_b32_e32 v101, 0
	v_mov_b32_e32 v94, 0
	v_mov_b32_e32 v95, 0
	v_mov_b32_e32 v96, 0
	v_mov_b32_e32 v97, 0
	v_mov_b32_e32 v90, 0
	v_mov_b32_e32 v91, 0
	v_mov_b32_e32 v92, 0
	v_mov_b32_e32 v93, 0
	v_mov_b32_e32 v86, 0
	v_mov_b32_e32 v87, 0
	v_mov_b32_e32 v88, 0
	v_mov_b32_e32 v89, 0
	v_mov_b32_e32 v82, 0
	v_mov_b32_e32 v83, 0
	v_mov_b32_e32 v84, 0
	v_mov_b32_e32 v85, 0
	v_mov_b32_e32 v78, 0
	v_mov_b32_e32 v79, 0
	v_mov_b32_e32 v80, 0
	v_mov_b32_e32 v81, 0
	v_mov_b32_e32 v62, 0
	v_mov_b32_e32 v63, 0
	v_mov_b32_e32 v64, 0
	v_mov_b32_e32 v65, 0
	v_mov_b32_e32 v58, 0
	v_mov_b32_e32 v59, 0
	v_mov_b32_e32 v60, 0
	v_mov_b32_e32 v61, 0
	v_mov_b32_e32 v46, 0
	v_mov_b32_e32 v47, 0
	v_mov_b32_e32 v48, 0
	v_mov_b32_e32 v49, 0
	v_mov_b32_e32 v42, 0
	v_mov_b32_e32 v43, 0
	v_mov_b32_e32 v44, 0
	v_mov_b32_e32 v45, 0
	v_mov_b32_e32 v38, 0
	v_mov_b32_e32 v39, 0
	v_mov_b32_e32 v40, 0
	v_mov_b32_e32 v41, 0
	v_mov_b32_e32 v34, 0
	v_mov_b32_e32 v35, 0
	v_mov_b32_e32 v36, 0
	v_mov_b32_e32 v37, 0
	v_mov_b32_e32 v30, 0
	v_mov_b32_e32 v31, 0
	v_mov_b32_e32 v32, 0
	v_mov_b32_e32 v33, 0
	v_mov_b32_e32 v26, 0
	v_mov_b32_e32 v27, 0
	v_mov_b32_e32 v28, 0
	v_mov_b32_e32 v29, 0
	v_mov_b32_e32 v22, 0
	v_mov_b32_e32 v23, 0
	v_mov_b32_e32 v24, 0
	v_mov_b32_e32 v25, 0
	v_mov_b32_e32 v18, 0
	v_mov_b32_e32 v19, 0
	v_mov_b32_e32 v20, 0
	v_mov_b32_e32 v21, 0
	v_mov_b32_e32 v14, 0
	v_mov_b32_e32 v15, 0
	v_mov_b32_e32 v16, 0
	v_mov_b32_e32 v17, 0
	v_mov_b32_e32 v10, 0
	v_mov_b32_e32 v11, 0
	v_mov_b32_e32 v12, 0
	v_mov_b32_e32 v13, 0
	v_mov_b32_e32 v6, 0
	v_mov_b32_e32 v7, 0
	v_mov_b32_e32 v8, 0
	v_mov_b32_e32 v9, 0
	v_mov_b32_e32 v2, 0
	v_mov_b32_e32 v3, 0
	v_mov_b32_e32 v4, 0
	v_mov_b32_e32 v5, 0
	s_mov_b32 s19, 0
	s_mov_b32 s5, 0
	s_waitcnt vmcnt(0)
	s_barrier

.Lipa_body:
	v_add_u32_e32 v183, s19, v182
	v_add_u32_e32 v200, v183, v180
	ds_read_b128 v[184:187], v200 offset:18432
	ds_read_b128 v[188:191], v200 offset:19456
	ds_read_b128 v[196:199], v200 offset:20480
	ds_read_b128 v[210:213], v200 offset:21504
	v_add_u32_e32 v183, v183, v181
	ds_read_b128 v[192:195], v183
	ds_read_b128 v[214:217], v183 offset:1024
	ds_read_b128 v[218:221], v183 offset:2048
	s_waitcnt lgkmcnt(2)
	v_mfma_f32_16x16x32_bf16 v[170:173], v[184:187], v[192:195], v[170:173]
	v_mfma_f32_16x16x32_bf16 v[166:169], v[188:191], v[192:195], v[166:169]
	v_mfma_f32_16x16x32_bf16 v[162:165], v[196:199], v[192:195], v[162:165]
	v_mfma_f32_16x16x32_bf16 v[158:161], v[210:213], v[192:195], v[158:161]
	ds_read_b128 v[192:195], v183 offset:3072
	s_waitcnt lgkmcnt(2)
	v_mfma_f32_16x16x32_bf16 v[154:157], v[184:187], v[214:217], v[154:157]
	v_mfma_f32_16x16x32_bf16 v[150:153], v[188:191], v[214:217], v[150:153]
	v_mfma_f32_16x16x32_bf16 v[146:149], v[196:199], v[214:217], v[146:149]
	v_mfma_f32_16x16x32_bf16 v[142:145], v[210:213], v[214:217], v[142:145]
	ds_read_b128 v[214:217], v183 offset:4096
	s_waitcnt lgkmcnt(2)
	v_mfma_f32_16x16x32_bf16 v[138:141], v[184:187], v[218:221], v[138:141]
	v_mfma_f32_16x16x32_bf16 v[134:137], v[188:191], v[218:221], v[134:137]
	v_mfma_f32_16x16x32_bf16 v[130:133], v[196:199], v[218:221], v[130:133]
	v_mfma_f32_16x16x32_bf16 v[126:129], v[210:213], v[218:221], v[126:129]
	ds_read_b128 v[218:221], v183 offset:5120
	s_waitcnt lgkmcnt(2)
	v_mfma_f32_16x16x32_bf16 v[122:125], v[184:187], v[192:195], v[122:125]
	v_mfma_f32_16x16x32_bf16 v[114:117], v[188:191], v[192:195], v[114:117]
	v_mfma_f32_16x16x32_bf16 v[110:113], v[196:199], v[192:195], v[110:113]
	v_mfma_f32_16x16x32_bf16 v[106:109], v[210:213], v[192:195], v[106:109]
	ds_read_b128 v[192:195], v183 offset:6144
	s_waitcnt lgkmcnt(2)
	v_mfma_f32_16x16x32_bf16 v[98:101], v[184:187], v[214:217], v[98:101]
	v_mfma_f32_16x16x32_bf16 v[94:97], v[188:191], v[214:217], v[94:97]
	v_mfma_f32_16x16x32_bf16 v[90:93], v[196:199], v[214:217], v[90:93]
	v_mfma_f32_16x16x32_bf16 v[86:89], v[210:213], v[214:217], v[86:89]
	ds_read_b128 v[214:217], v183 offset:7168
	s_waitcnt lgkmcnt(2)
	v_mfma_f32_16x16x32_bf16 v[82:85], v[184:187], v[218:221], v[82:85]
	v_mfma_f32_16x16x32_bf16 v[78:81], v[188:191], v[218:221], v[78:81]
	v_mfma_f32_16x16x32_bf16 v[62:65], v[196:199], v[218:221], v[62:65]
	v_mfma_f32_16x16x32_bf16 v[58:61], v[210:213], v[218:221], v[58:61]
	ds_read_b128 v[218:221], v183 offset:8192
	s_waitcnt lgkmcnt(2)
	v_mfma_f32_16x16x32_bf16 v[46:49], v[184:187], v[192:195], v[46:49]
	v_mfma_f32_16x16x32_bf16 v[42:45], v[188:191], v[192:195], v[42:45]
	v_mfma_f32_16x16x32_bf16 v[38:41], v[196:199], v[192:195], v[38:41]
	v_mfma_f32_16x16x32_bf16 v[34:37], v[210:213], v[192:195], v[34:37]
	s_waitcnt lgkmcnt(1)
	v_mfma_f32_16x16x32_bf16 v[30:33], v[184:187], v[214:217], v[30:33]
	v_mfma_f32_16x16x32_bf16 v[26:29], v[188:191], v[214:217], v[26:29]
	v_mfma_f32_16x16x32_bf16 v[22:25], v[196:199], v[214:217], v[22:25]
	v_mfma_f32_16x16x32_bf16 v[18:21], v[210:213], v[214:217], v[18:21]
	s_waitcnt lgkmcnt(0)
	v_mfma_f32_16x16x32_bf16 v[14:17], v[184:187], v[218:221], v[14:17]
	v_mfma_f32_16x16x32_bf16 v[10:13], v[188:191], v[218:221], v[10:13]
	v_mfma_f32_16x16x32_bf16 v[6:9], v[196:199], v[218:221], v[6:9]
	v_mfma_f32_16x16x32_bf16 v[2:5], v[210:213], v[218:221], v[2:5]
	s_xor_b32 s19, s19, 26624
	s_waitcnt vmcnt(0)
	s_barrier
	s_add_u32 s5, s5, 1
	s_cmp_lt_u32 s5, 32
	s_cbranch_scc1 .Lipa_loop

.LBB0_731:
	s_and_b64 vcc, exec, s[0:1]
	s_cbranch_vccz .LBB0_693
	v_readfirstlane_b32 s13, v175
	v_lshrrev_b32_e32 v43, 3, v175
	v_and_b32_e32 v43, 6, v43
	s_movk_i32 s16, 0x78
	v_lshrrev_b32_e64 v43, v43, s16
	v_xor_b32_e32 v43, v43, v175
	v_and_b32_e32 v43, 3, v43
	v_lshlrev_b32_e32 v43, 4, v43
	v_lshrrev_b32_e32 v44, 2, v175
	v_lshl_or_b32 v38, v44, 11, v43
	v_add_u32_e32 v39, 0x20000, v38
	v_add_u32_e32 v40, 0x40000, v38
	v_add_u32_e32 v41, 0x60000, v38
	v_add_u32_e32 v42, 0x80000, v38
	s_lshl_b32 s16, s12, 11
	s_add_u32 s6, s96, s16
	s_addc_u32 s7, s97, 0
	v_readlane_b32 s8, v252, 52
	v_readlane_b32 s9, v252, 53
	s_lshl_b32 s16, s14, 11
	s_add_u32 s8, s8, s16
	s_addc_u32 s9, s9, 0
	s_lshr_b32 s16, s13, 6
	s_lshl_b32 s18, s16, 10
	s_cmpk_lt_i32 s13, 0x80
	s_cselect_b32 s15, 1, 0
	s_mov_b32 m0, s18
	s_nop 0
	global_load_lds_dwordx4 v38, s[6:7]
	s_add_u32 m0, s18, 4096
	s_nop 0
	global_load_lds_dwordx4 v39, s[6:7]
	s_add_u32 m0, s18, 8192
	s_nop 0
	global_load_lds_dwordx4 v40, s[6:7]
	s_add_u32 m0, s18, 12288
	s_nop 0
	global_load_lds_dwordx4 v41, s[6:7]
	s_cmp_eq_u32 s15, 0
	s_cbranch_scc1 .Lipb_noremp
	s_add_u32 m0, s18, 16384
	s_nop 0
	global_load_lds_dwordx4 v42, s[6:7]
.Lipb_noremp:
	s_add_u32 m0, s18, 18432
	s_nop 0
	global_load_lds_dwordx4 v38, s[8:9]
	s_add_u32 m0, s18, 22528
	s_nop 0
	global_load_lds_dwordx4 v39, s[8:9]
	s_add_u32 s6, s6, 64
	s_addc_u32 s7, s7, 0
	s_add_u32 s8, s8, 64
	s_addc_u32 s9, s9, 0
	s_add_u32 s18, s18, 26624
	s_cmp_ge_u32 s18, 53248
	s_cselect_b32 s16, 53248, 0
	s_sub_u32 s18, s18, s16
	v_and_b32_e32 v43, 15, v175
	s_and_b32 s16, s13, 64
	v_or_b32_e32 v44, s16, v43
	v_lshlrev_b32_e32 v180, 6, v44
	s_ashr_i32 s16, s13, 7
	s_mulk_i32 s16, 0x90
	v_or_b32_e32 v44, s16, v43
	v_lshlrev_b32_e32 v181, 6, v44
	v_lshrrev_b32_e32 v44, 1, v175
	v_and_b32_e32 v44, 6, v44
	s_movk_i32 s16, 0x78
	v_lshrrev_b32_e64 v44, v44, s16
	v_lshrrev_b32_e32 v45, 4, v175
	v_xor_b32_e32 v44, v44, v45
	v_lshlrev_b32_e32 v44, 4, v44
	v_and_b32_e32 v182, 48, v44
	v_mov_b32_e32 v170, 0
	v_mov_b32_e32 v171, 0
	v_mov_b32_e32 v172, 0
	v_mov_b32_e32 v173, 0
	v_mov_b32_e32 v154, 0
	v_mov_b32_e32 v155, 0
	v_mov_b32_e32 v156, 0
	v_mov_b32_e32 v157, 0
	v_mov_b32_e32 v122, 0
	v_mov_b32_e32 v123, 0
	v_mov_b32_e32 v124, 0
	v_mov_b32_e32 v125, 0
	v_mov_b32_e32 v82, 0
	v_mov_b32_e32 v83, 0
	v_mov_b32_e32 v84, 0
	v_mov_b32_e32 v85, 0
	v_mov_b32_e32 v166, 0
	v_mov_b32_e32 v167, 0
	v_mov_b32_e32 v168, 0
	v_mov_b32_e32 v169, 0
	v_mov_b32_e32 v150, 0
	v_mov_b32_e32 v151, 0
	v_mov_b32_e32 v152, 0
	v_mov_b32_e32 v153, 0
	v_mov_b32_e32 v114, 0
	v_mov_b32_e32 v115, 0
	v_mov_b32_e32 v116, 0
	v_mov_b32_e32 v117, 0
	v_mov_b32_e32 v74, 0
	v_mov_b32_e32 v75, 0
	v_mov_b32_e32 v76, 0
	v_mov_b32_e32 v77, 0
	v_mov_b32_e32 v162, 0
	v_mov_b32_e32 v163, 0
	v_mov_b32_e32 v164, 0
	v_mov_b32_e32 v165, 0
	v_mov_b32_e32 v138, 0
	v_mov_b32_e32 v139, 0
	v_mov_b32_e32 v140, 0
	v_mov_b32_e32 v141, 0
	v_mov_b32_e32 v94, 0
	v_mov_b32_e32 v95, 0
	v_mov_b32_e32 v96, 0
	v_mov_b32_e32 v97, 0
	v_mov_b32_e32 v46, 0
	v_mov_b32_e32 v47, 0
	v_mov_b32_e32 v48, 0
	v_mov_b32_e32 v49, 0
	v_mov_b32_e32 v158, 0
	v_mov_b32_e32 v159, 0
	v_mov_b32_e32 v160, 0
	v_mov_b32_e32 v161, 0
	v_mov_b32_e32 v134, 0
	v_mov_b32_e32 v135, 0
	v_mov_b32_e32 v136, 0
	v_mov_b32_e32 v137, 0
	v_mov_b32_e32 v90, 0
	v_mov_b32_e32 v91, 0
	v_mov_b32_e32 v92, 0
	v_mov_b32_e32 v93, 0
	v_mov_b32_e32 v34, 0
	v_mov_b32_e32 v35, 0
	v_mov_b32_e32 v36, 0
	v_mov_b32_e32 v37, 0
	v_mov_b32_e32 v146, 0
	v_mov_b32_e32 v147, 0
	v_mov_b32_e32 v148, 0
	v_mov_b32_e32 v149, 0
	v_mov_b32_e32 v110, 0
	v_mov_b32_e32 v111, 0
	v_mov_b32_e32 v112, 0
	v_mov_b32_e32 v113, 0
	v_mov_b32_e32 v70, 0
	v_mov_b32_e32 v71, 0
	v_mov_b32_e32 v72, 0
	v_mov_b32_e32 v73, 0
	v_mov_b32_e32 v22, 0
	v_mov_b32_e32 v23, 0
	v_mov_b32_e32 v24, 0
	v_mov_b32_e32 v25, 0
	v_mov_b32_e32 v142, 0
	v_mov_b32_e32 v143, 0
	v_mov_b32_e32 v144, 0
	v_mov_b32_e32 v145, 0
	v_mov_b32_e32 v102, 0
	v_mov_b32_e32 v103, 0
	v_mov_b32_e32 v104, 0
	v_mov_b32_e32 v105, 0
	v_mov_b32_e32 v54, 0
	v_mov_b32_e32 v55, 0
	v_mov_b32_e32 v56, 0
	v_mov_b32_e32 v57, 0
	v_mov_b32_e32 v18, 0
	v_mov_b32_e32 v19, 0
	v_mov_b32_e32 v20, 0
	v_mov_b32_e32 v21, 0
	v_mov_b32_e32 v130, 0
	v_mov_b32_e32 v131, 0
	v_mov_b32_e32 v132, 0
	v_mov_b32_e32 v133, 0
	v_mov_b32_e32 v86, 0
	v_mov_b32_e32 v87, 0
	v_mov_b32_e32 v88, 0
	v_mov_b32_e32 v89, 0
	v_mov_b32_e32 v30, 0
	v_mov_b32_e32 v31, 0
	v_mov_b32_e32 v32, 0
	v_mov_b32_e32 v33, 0
	v_mov_b32_e32 v10, 0
	v_mov_b32_e32 v11, 0
	v_mov_b32_e32 v12, 0
	v_mov_b32_e32 v13, 0
	v_mov_b32_e32 v118, 0
	v_mov_b32_e32 v119, 0
	v_mov_b32_e32 v120, 0
	v_mov_b32_e32 v121, 0
	v_mov_b32_e32 v78, 0
	v_mov_b32_e32 v79, 0
	v_mov_b32_e32 v80, 0
	v_mov_b32_e32 v81, 0
	v_mov_b32_e32 v26, 0
	v_mov_b32_e32 v27, 0
	v_mov_b32_e32 v28, 0
	v_mov_b32_e32 v29, 0
	v_mov_b32_e32 v6, 0
	v_mov_b32_e32 v7, 0
	v_mov_b32_e32 v8, 0
	v_mov_b32_e32 v9, 0
	v_mov_b32_e32 v98, 0
	v_mov_b32_e32 v99, 0
	v_mov_b32_e32 v100, 0
	v_mov_b32_e32 v101, 0
	v_mov_b32_e32 v50, 0
	v_mov_b32_e32 v51, 0
	v_mov_b32_e32 v52, 0
	v_mov_b32_e32 v53, 0
	v_mov_b32_e32 v14, 0
	v_mov_b32_e32 v15, 0
	v_mov_b32_e32 v16, 0
	v_mov_b32_e32 v17, 0
	v_mov_b32_e32 v2, 0
	v_mov_b32_e32 v3, 0
	v_mov_b32_e32 v4, 0
	v_mov_b32_e32 v5, 0
	s_mov_b32 s19, 0
	s_mov_b32 s5, 0
	s_waitcnt vmcnt(0)
	s_barrier

.Lipb_body:
	v_add_u32_e32 v183, s19, v182
	v_add_u32_e32 v200, v183, v181
	ds_read_b128 v[184:187], v200
	ds_read_b128 v[214:217], v200 offset:1024
	ds_read_b128 v[218:221], v200 offset:2048
	v_add_u32_e32 v183, v183, v180
	ds_read_b128 v[188:191], v183 offset:18432
	ds_read_b128 v[192:195], v183 offset:19456
	ds_read_b128 v[196:199], v183 offset:20480
	ds_read_b128 v[210:213], v183 offset:21504
	s_waitcnt lgkmcnt(3)
	v_mfma_f32_16x16x32_bf16 v[170:173], v[184:187], v[188:191], v[170:173]
	s_waitcnt lgkmcnt(2)
	v_mfma_f32_16x16x32_bf16 v[154:157], v[184:187], v[192:195], v[154:157]
	s_waitcnt lgkmcnt(1)
	v_mfma_f32_16x16x32_bf16 v[122:125], v[184:187], v[196:199], v[122:125]
	s_waitcnt lgkmcnt(0)
	v_mfma_f32_16x16x32_bf16 v[82:85], v[184:187], v[210:213], v[82:85]
	ds_read_b128 v[184:187], v200 offset:3072
	v_mfma_f32_16x16x32_bf16 v[166:169], v[214:217], v[188:191], v[166:169]
	v_mfma_f32_16x16x32_bf16 v[150:153], v[214:217], v[192:195], v[150:153]
	v_mfma_f32_16x16x32_bf16 v[114:117], v[214:217], v[196:199], v[114:117]
	v_mfma_f32_16x16x32_bf16 v[74:77], v[214:217], v[210:213], v[74:77]
	ds_read_b128 v[214:217], v200 offset:4096
	v_mfma_f32_16x16x32_bf16 v[162:165], v[218:221], v[188:191], v[162:165]
	v_mfma_f32_16x16x32_bf16 v[138:141], v[218:221], v[192:195], v[138:141]
	v_mfma_f32_16x16x32_bf16 v[94:97], v[218:221], v[196:199], v[94:97]
	v_mfma_f32_16x16x32_bf16 v[46:49], v[218:221], v[210:213], v[46:49]
	ds_read_b128 v[218:221], v200 offset:5120
	s_waitcnt lgkmcnt(2)
	v_mfma_f32_16x16x32_bf16 v[158:161], v[184:187], v[188:191], v[158:161]
	v_mfma_f32_16x16x32_bf16 v[134:137], v[184:187], v[192:195], v[134:137]
	v_mfma_f32_16x16x32_bf16 v[90:93], v[184:187], v[196:199], v[90:93]
	v_mfma_f32_16x16x32_bf16 v[34:37], v[184:187], v[210:213], v[34:37]
	ds_read_b128 v[184:187], v200 offset:6144
	s_waitcnt lgkmcnt(2)
	v_mfma_f32_16x16x32_bf16 v[146:149], v[214:217], v[188:191], v[146:149]
	v_mfma_f32_16x16x32_bf16 v[110:113], v[214:217], v[192:195], v[110:113]
	v_mfma_f32_16x16x32_bf16 v[70:73], v[214:217], v[196:199], v[70:73]
	v_mfma_f32_16x16x32_bf16 v[22:25], v[214:217], v[210:213], v[22:25]
	ds_read_b128 v[214:217], v200 offset:7168
	s_waitcnt lgkmcnt(2)
	v_mfma_f32_16x16x32_bf16 v[142:145], v[218:221], v[188:191], v[142:145]
	v_mfma_f32_16x16x32_bf16 v[102:105], v[218:221], v[192:195], v[102:105]
	v_mfma_f32_16x16x32_bf16 v[54:57], v[218:221], v[196:199], v[54:57]
	v_mfma_f32_16x16x32_bf16 v[18:21], v[218:221], v[210:213], v[18:21]
	ds_read_b128 v[218:221], v200 offset:8192
	s_waitcnt lgkmcnt(2)
	v_mfma_f32_16x16x32_bf16 v[130:133], v[184:187], v[188:191], v[130:133]
	v_mfma_f32_16x16x32_bf16 v[86:89], v[184:187], v[192:195], v[86:89]
	v_mfma_f32_16x16x32_bf16 v[30:33], v[184:187], v[196:199], v[30:33]
	v_mfma_f32_16x16x32_bf16 v[10:13], v[184:187], v[210:213], v[10:13]
	s_waitcnt lgkmcnt(1)
	v_mfma_f32_16x16x32_bf16 v[118:121], v[214:217], v[188:191], v[118:121]
	v_mfma_f32_16x16x32_bf16 v[78:81], v[214:217], v[192:195], v[78:81]
	v_mfma_f32_16x16x32_bf16 v[26:29], v[214:217], v[196:199], v[26:29]
	v_mfma_f32_16x16x32_bf16 v[6:9], v[214:217], v[210:213], v[6:9]
	s_waitcnt lgkmcnt(0)
	v_mfma_f32_16x16x32_bf16 v[98:101], v[218:221], v[188:191], v[98:101]
	v_mfma_f32_16x16x32_bf16 v[50:53], v[218:221], v[192:195], v[50:53]
	v_mfma_f32_16x16x32_bf16 v[14:17], v[218:221], v[196:199], v[14:17]
	v_mfma_f32_16x16x32_bf16 v[2:5], v[218:221], v[210:213], v[2:5]
	s_xor_b32 s19, s19, 26624
	s_waitcnt vmcnt(0)
	s_barrier
	s_add_u32 s5, s5, 1
	s_cmp_lt_u32 s5, 32
	s_cbranch_scc1 .Lipb_loop
	s_branch .LBB0_692

.LBB0_881:
	s_lshl_b32 s0, s8, 3
	s_and_b32 s0, s0, 56
	s_ashr_i32 s4, s8, 6
	s_add_i32 s9, s0, s4
	s_mulk_i32 s9, 0x120
	s_lshl_b32 s0, s8, 4
	s_and_b32 s10, s0, 0x380
	v_readfirstlane_b32 s1, v175
	v_lshrrev_b32_e32 v135, 3, v175
	v_and_b32_e32 v135, 6, v135
	s_movk_i32 s0, 0x78
	v_lshrrev_b32_e64 v135, v135, s0
	v_xor_b32_e32 v135, v135, v175
	v_and_b32_e32 v135, 3, v135
	v_lshlrev_b32_e32 v135, 4, v135
	v_lshrrev_b32_e32 v136, 2, v175
	v_lshl_or_b32 v130, v136, 11, v135
	v_add_u32_e32 v131, 0x20000, v130
	v_add_u32_e32 v132, 0x40000, v130
	v_add_u32_e32 v133, 0x60000, v130
	v_add_u32_e32 v134, 0x80000, v130
	s_lshl_b32 s0, s9, 11
	s_add_u32 s2, s96, s0
	s_addc_u32 s3, s97, 0
	s_lshl_b32 s0, s10, 11
	s_add_u32 s4, s30, s0
	s_addc_u32 s5, s31, 0
	s_lshr_b32 s0, s1, 6
	s_lshl_b32 s12, s0, 10
	s_cmpk_lt_i32 s1, 0x80
	s_cselect_b32 s100, 1, 0
	s_mov_b32 m0, s12
	s_nop 0
	global_load_lds_dwordx4 v130, s[2:3]
	s_add_u32 m0, s12, 4096
	s_nop 0
	global_load_lds_dwordx4 v131, s[2:3]
	s_add_u32 m0, s12, 8192
	s_nop 0
	global_load_lds_dwordx4 v132, s[2:3]
	s_add_u32 m0, s12, 12288
	s_nop 0
	global_load_lds_dwordx4 v133, s[2:3]
	s_cmp_eq_u32 s100, 0
	s_cbranch_scc1 .Lop9_noremp
	s_add_u32 m0, s12, 16384
	s_nop 0
	global_load_lds_dwordx4 v134, s[2:3]
.Lop9_noremp:
	s_add_u32 m0, s12, 18432
	s_nop 0
	global_load_lds_dwordx4 v130, s[4:5]
	s_add_u32 m0, s12, 22528
	s_nop 0
	global_load_lds_dwordx4 v131, s[4:5]
	s_add_u32 s2, s2, 64
	s_addc_u32 s3, s3, 0
	s_add_u32 s4, s4, 64
	s_addc_u32 s5, s5, 0
	s_add_u32 s12, s12, 26624
	s_cmp_ge_u32 s12, 53248
	s_cselect_b32 s0, 53248, 0
	s_sub_u32 s12, s12, s0
	v_and_b32_e32 v135, 15, v175
	s_and_b32 s0, s1, 64
	v_or_b32_e32 v136, s0, v135
	v_lshlrev_b32_e32 v180, 6, v136
	s_ashr_i32 s0, s1, 7
	s_mulk_i32 s0, 0x90
	v_or_b32_e32 v136, s0, v135
	v_lshlrev_b32_e32 v181, 6, v136
	v_lshrrev_b32_e32 v136, 1, v175
	v_and_b32_e32 v136, 6, v136
	s_movk_i32 s0, 0x78
	v_lshrrev_b32_e64 v136, v136, s0
	v_lshrrev_b32_e32 v137, 4, v175
	v_xor_b32_e32 v136, v136, v137
	v_lshlrev_b32_e32 v136, 4, v136
	v_and_b32_e32 v182, 48, v136
	v_mov_b32_e32 v170, 0
	v_mov_b32_e32 v171, 0
	v_mov_b32_e32 v172, 0
	v_mov_b32_e32 v173, 0
	v_mov_b32_e32 v162, 0
	v_mov_b32_e32 v163, 0
	v_mov_b32_e32 v164, 0
	v_mov_b32_e32 v165, 0
	v_mov_b32_e32 v158, 0
	v_mov_b32_e32 v159, 0
	v_mov_b32_e32 v160, 0
	v_mov_b32_e32 v161, 0
	v_mov_b32_e32 v150, 0
	v_mov_b32_e32 v151, 0
	v_mov_b32_e32 v152, 0
	v_mov_b32_e32 v153, 0
	v_mov_b32_e32 v126, 0
	v_mov_b32_e32 v127, 0
	v_mov_b32_e32 v128, 0
	v_mov_b32_e32 v129, 0
	v_mov_b32_e32 v122, 0
	v_mov_b32_e32 v123, 0
	v_mov_b32_e32 v124, 0
	v_mov_b32_e32 v125, 0
	v_mov_b32_e32 v118, 0
	v_mov_b32_e32 v119, 0
	v_mov_b32_e32 v120, 0
	v_mov_b32_e32 v121, 0
	v_mov_b32_e32 v114, 0
	v_mov_b32_e32 v115, 0
	v_mov_b32_e32 v116, 0
	v_mov_b32_e32 v117, 0
	v_mov_b32_e32 v110, 0
	v_mov_b32_e32 v111, 0
	v_mov_b32_e32 v112, 0
	v_mov_b32_e32 v113, 0
	v_mov_b32_e32 v106, 0
	v_mov_b32_e32 v107, 0
	v_mov_b32_e32 v108, 0
	v_mov_b32_e32 v109, 0
	v_mov_b32_e32 v102, 0
	v_mov_b32_e32 v103, 0
	v_mov_b32_e32 v104, 0
	v_mov_b32_e32 v105, 0
	v_mov_b32_e32 v98, 0
	v_mov_b32_e32 v99, 0
	v_mov_b32_e32 v100, 0
	v_mov_b32_e32 v101, 0
	v_mov_b32_e32 v94, 0
	v_mov_b32_e32 v95, 0
	v_mov_b32_e32 v96, 0
	v_mov_b32_e32 v97, 0
	v_mov_b32_e32 v90, 0
	v_mov_b32_e32 v91, 0
	v_mov_b32_e32 v92, 0
	v_mov_b32_e32 v93, 0
	v_mov_b32_e32 v86, 0
	v_mov_b32_e32 v87, 0
	v_mov_b32_e32 v88, 0
	v_mov_b32_e32 v89, 0
	v_mov_b32_e32 v82, 0
	v_mov_b32_e32 v83, 0
	v_mov_b32_e32 v84, 0
	v_mov_b32_e32 v85, 0
	v_mov_b32_e32 v78, 0
	v_mov_b32_e32 v79, 0
	v_mov_b32_e32 v80, 0
	v_mov_b32_e32 v81, 0
	v_mov_b32_e32 v74, 0
	v_mov_b32_e32 v75, 0
	v_mov_b32_e32 v76, 0
	v_mov_b32_e32 v77, 0
	v_mov_b32_e32 v70, 0
	v_mov_b32_e32 v71, 0
	v_mov_b32_e32 v72, 0
	v_mov_b32_e32 v73, 0
	v_mov_b32_e32 v66, 0
	v_mov_b32_e32 v67, 0
	v_mov_b32_e32 v68, 0
	v_mov_b32_e32 v69, 0
	v_mov_b32_e32 v62, 0
	v_mov_b32_e32 v63, 0
	v_mov_b32_e32 v64, 0
	v_mov_b32_e32 v65, 0
	v_mov_b32_e32 v58, 0
	v_mov_b32_e32 v59, 0
	v_mov_b32_e32 v60, 0
	v_mov_b32_e32 v61, 0
	v_mov_b32_e32 v54, 0
	v_mov_b32_e32 v55, 0
	v_mov_b32_e32 v56, 0
	v_mov_b32_e32 v57, 0
	v_mov_b32_e32 v50, 0
	v_mov_b32_e32 v51, 0
	v_mov_b32_e32 v52, 0
	v_mov_b32_e32 v53, 0
	v_mov_b32_e32 v46, 0
	v_mov_b32_e32 v47, 0
	v_mov_b32_e32 v48, 0
	v_mov_b32_e32 v49, 0
	v_mov_b32_e32 v42, 0
	v_mov_b32_e32 v43, 0
	v_mov_b32_e32 v44, 0
	v_mov_b32_e32 v45, 0
	v_mov_b32_e32 v38, 0
	v_mov_b32_e32 v39, 0
	v_mov_b32_e32 v40, 0
	v_mov_b32_e32 v41, 0
	v_mov_b32_e32 v34, 0
	v_mov_b32_e32 v35, 0
	v_mov_b32_e32 v36, 0
	v_mov_b32_e32 v37, 0
	v_mov_b32_e32 v30, 0
	v_mov_b32_e32 v31, 0
	v_mov_b32_e32 v32, 0
	v_mov_b32_e32 v33, 0
	v_mov_b32_e32 v26, 0
	v_mov_b32_e32 v27, 0
	v_mov_b32_e32 v28, 0
	v_mov_b32_e32 v29, 0
	v_mov_b32_e32 v22, 0
	v_mov_b32_e32 v23, 0
	v_mov_b32_e32 v24, 0
	v_mov_b32_e32 v25, 0
	v_mov_b32_e32 v18, 0
	v_mov_b32_e32 v19, 0
	v_mov_b32_e32 v20, 0
	v_mov_b32_e32 v21, 0
	v_mov_b32_e32 v14, 0
	v_mov_b32_e32 v15, 0
	v_mov_b32_e32 v16, 0
	v_mov_b32_e32 v17, 0
	v_mov_b32_e32 v10, 0
	v_mov_b32_e32 v11, 0
	v_mov_b32_e32 v12, 0
	v_mov_b32_e32 v13, 0
	v_mov_b32_e32 v6, 0
	v_mov_b32_e32 v7, 0
	v_mov_b32_e32 v8, 0
	v_mov_b32_e32 v9, 0
	v_mov_b32_e32 v2, 0
	v_mov_b32_e32 v3, 0
	v_mov_b32_e32 v4, 0
	v_mov_b32_e32 v5, 0
	s_mov_b32 s13, 0
	s_mov_b32 s11, 0
	s_waitcnt vmcnt(0)
	s_barrier
.Lop9_loop:
	s_cmp_ge_u32 s11, 31
	s_cbranch_scc1 .Lop9_body
	s_mov_b32 m0, s12
	s_nop 0
	global_load_lds_dwordx4 v130, s[2:3]
	s_add_u32 m0, s12, 4096
	s_nop 0
	global_load_lds_dwordx4 v131, s[2:3]
	s_add_u32 m0, s12, 8192
	s_nop 0
	global_load_lds_dwordx4 v132, s[2:3]
	s_add_u32 m0, s12, 12288
	s_nop 0
	global_load_lds_dwordx4 v133, s[2:3]
	s_cmp_eq_u32 s100, 0
	s_cbranch_scc1 .Lop9_noreml
	s_add_u32 m0, s12, 16384
	s_nop 0
	global_load_lds_dwordx4 v134, s[2:3]
.Lop9_noreml:
	s_add_u32 m0, s12, 18432
	s_nop 0
	global_load_lds_dwordx4 v130, s[4:5]
	s_add_u32 m0, s12, 22528
	s_nop 0
	global_load_lds_dwordx4 v131, s[4:5]
	s_add_u32 s2, s2, 64
	s_addc_u32 s3, s3, 0
	s_add_u32 s4, s4, 64
	s_addc_u32 s5, s5, 0
	s_add_u32 s12, s12, 26624
	s_cmp_ge_u32 s12, 53248
	s_cselect_b32 s0, 53248, 0
	s_sub_u32 s12, s12, s0
.Lop9_body:
	v_add_u32_e32 v183, s13, v182
	v_add_u32_e32 v200, v183, v180
	ds_read_b128 v[184:187], v200 offset:18432
	ds_read_b128 v[188:191], v200 offset:19456
	ds_read_b128 v[196:199], v200 offset:20480
	ds_read_b128 v[200:203], v200 offset:21504
	v_add_u32_e32 v183, v183, v181
	ds_read_b128 v[192:195], v183
	ds_read_b128 v[208:211], v183 offset:1024
	ds_read_b128 v[212:215], v183 offset:2048
	s_waitcnt lgkmcnt(2)
	v_mfma_f32_16x16x32_bf16 v[170:173], v[184:187], v[192:195], v[170:173]
	v_mfma_f32_16x16x32_bf16 v[162:165], v[188:191], v[192:195], v[162:165]
	v_mfma_f32_16x16x32_bf16 v[158:161], v[196:199], v[192:195], v[158:161]
	v_mfma_f32_16x16x32_bf16 v[150:153], v[200:203], v[192:195], v[150:153]
	ds_read_b128 v[192:195], v183 offset:3072
	s_waitcnt lgkmcnt(2)
	v_mfma_f32_16x16x32_bf16 v[126:129], v[184:187], v[208:211], v[126:129]
	v_mfma_f32_16x16x32_bf16 v[122:125], v[188:191], v[208:211], v[122:125]
	v_mfma_f32_16x16x32_bf16 v[118:121], v[196:199], v[208:211], v[118:121]
	v_mfma_f32_16x16x32_bf16 v[114:117], v[200:203], v[208:211], v[114:117]
	ds_read_b128 v[208:211], v183 offset:4096
	s_waitcnt lgkmcnt(2)
	v_mfma_f32_16x16x32_bf16 v[110:113], v[184:187], v[212:215], v[110:113]
	v_mfma_f32_16x16x32_bf16 v[106:109], v[188:191], v[212:215], v[106:109]
	v_mfma_f32_16x16x32_bf16 v[102:105], v[196:199], v[212:215], v[102:105]
	v_mfma_f32_16x16x32_bf16 v[98:101], v[200:203], v[212:215], v[98:101]
	ds_read_b128 v[212:215], v183 offset:5120
	s_waitcnt lgkmcnt(2)
	v_mfma_f32_16x16x32_bf16 v[94:97], v[184:187], v[192:195], v[94:97]
	v_mfma_f32_16x16x32_bf16 v[90:93], v[188:191], v[192:195], v[90:93]
	v_mfma_f32_16x16x32_bf16 v[86:89], v[196:199], v[192:195], v[86:89]
	v_mfma_f32_16x16x32_bf16 v[82:85], v[200:203], v[192:195], v[82:85]
	ds_read_b128 v[192:195], v183 offset:6144
	s_waitcnt lgkmcnt(2)
	v_mfma_f32_16x16x32_bf16 v[78:81], v[184:187], v[208:211], v[78:81]
	v_mfma_f32_16x16x32_bf16 v[74:77], v[188:191], v[208:211], v[74:77]
	v_mfma_f32_16x16x32_bf16 v[70:73], v[196:199], v[208:211], v[70:73]
	v_mfma_f32_16x16x32_bf16 v[66:69], v[200:203], v[208:211], v[66:69]
	ds_read_b128 v[208:211], v183 offset:7168
	s_waitcnt lgkmcnt(2)
	v_mfma_f32_16x16x32_bf16 v[62:65], v[184:187], v[212:215], v[62:65]
	v_mfma_f32_16x16x32_bf16 v[58:61], v[188:191], v[212:215], v[58:61]
	v_mfma_f32_16x16x32_bf16 v[54:57], v[196:199], v[212:215], v[54:57]
	v_mfma_f32_16x16x32_bf16 v[50:53], v[200:203], v[212:215], v[50:53]
	ds_read_b128 v[212:215], v183 offset:8192
	s_waitcnt lgkmcnt(2)
	v_mfma_f32_16x16x32_bf16 v[46:49], v[184:187], v[192:195], v[46:49]
	v_mfma_f32_16x16x32_bf16 v[42:45], v[188:191], v[192:195], v[42:45]
	v_mfma_f32_16x16x32_bf16 v[38:41], v[196:199], v[192:195], v[38:41]
	v_mfma_f32_16x16x32_bf16 v[34:37], v[200:203], v[192:195], v[34:37]
	s_waitcnt lgkmcnt(1)
	v_mfma_f32_16x16x32_bf16 v[30:33], v[184:187], v[208:211], v[30:33]
	v_mfma_f32_16x16x32_bf16 v[26:29], v[188:191], v[208:211], v[26:29]
	v_mfma_f32_16x16x32_bf16 v[22:25], v[196:199], v[208:211], v[22:25]
	v_mfma_f32_16x16x32_bf16 v[18:21], v[200:203], v[208:211], v[18:21]
	s_waitcnt lgkmcnt(0)
	v_mfma_f32_16x16x32_bf16 v[14:17], v[184:187], v[212:215], v[14:17]
	v_mfma_f32_16x16x32_bf16 v[10:13], v[188:191], v[212:215], v[10:13]
	v_mfma_f32_16x16x32_bf16 v[6:9], v[196:199], v[212:215], v[6:9]
	v_mfma_f32_16x16x32_bf16 v[2:5], v[200:203], v[212:215], v[2:5]
	s_xor_b32 s13, s13, 26624
	s_waitcnt vmcnt(0)
	s_barrier
	s_add_u32 s11, s11, 1
	s_cmp_lt_u32 s11, 32
	s_cbranch_scc1 .Lop9_loop
	s_branch .LBB0_880
